# EpiResid row sum-of-squares: xor-16 / xor-32 lane reductions via v_permlane16_swap / v_permlane32_swap instead of ds_bpermute + full LDS wait
# baseline (speedup 1.0000x reference)
; __device__ __forceinline__ unsigned cvt_pk_bf16(float lo, float hi) { unsigned r; asm volatile("v_cvt_pk_bf16_f32 %0, %1, %2" : "=v"(r) : "v"(lo), "v"(hi)); return r; }
;     __device__ __forceinline__ void operator()(const f32x4 (&acc)[2][2][4][2], const Unit& u, int wr, int wc, int fr, int fq) const {
;         const int row0 = u.pm * BM + wr * 64 + fr, col0 = u.pn * BM + wc * 32 + 8 * fq;
;         u32x4 hv[2][4][2];
; #pragma unroll
;         for (int ai = 0; ai < 2; ++ai)
; #pragma unroll
;             for (int m = 0; m < 4; ++m)
; #pragma unroll
;                 for (int bj = 0; bj < 2; ++bj) hv[ai][m][bj] = *(const u32x4*)(hb + (size_t)(row0 + ai * HALF + m * 16) * 1024 + col0 + bj * HALF);
; #pragma unroll
;         for (int ai = 0; ai < 2; ++ai)
; #pragma unroll
;             for (int m = 0; m < 4; ++m) { const int row = row0 + ai * HALF + m * 16; float s = 0.f;
; #pragma unroll
;                 for (int bj = 0; bj < 2; ++bj) { const size_t off = (size_t)row * 1024 + col0 + bj * HALF;
;                     const u32x4 h4 = hv[ai][m][bj];
;                     const f32x4 b0 = {__uint_as_float(h4.x << 16), __uint_as_float(h4.x & 0xffff0000u), __uint_as_float(h4.y << 16), __uint_as_float(h4.y & 0xffff0000u)};
;                     const f32x4 b1 = {__uint_as_float(h4.z << 16), __uint_as_float(h4.z & 0xffff0000u), __uint_as_float(h4.w << 16), __uint_as_float(h4.w & 0xffff0000u)};
;                     const f32x4 v0 = acc[ai][bj][m][0] + b0, v1 = acc[ai][bj][m][1] + b1;
;                     u32x4 w; w.x = cvt_pk_bf16(v0[0], v0[1]); w.y = cvt_pk_bf16(v0[2], v0[3]); w.z = cvt_pk_bf16(v1[0], v1[1]); w.w = cvt_pk_bf16(v1[2], v1[3]);
;                     *(u32x4*)(hb + off) = w;
;                     s += ((v0[0] * v0[0] + v0[1] * v0[1]) + (v0[2] * v0[2] + v0[3] * v0[3])) + ((v1[0] * v1[0] + v1[1] * v1[1]) + (v1[2] * v1[2] + v1[3] * v1[3])); }
;                 s += __shfl_xor(s, 16); s += __shfl_xor(s, 32);
;                 if (fq == 0) ssq[(size_t)row * 16 + u.pn * 4 + wc] = s; }
.LBB0_323:
	v_lshl_or_b32 v204, s12, 8, v253
	v_lshl_add_u32 v240, s61, 8, v251
	v_ashrrev_i32_e32 v205, 31, v204
	v_lshlrev_b64 v[242:243], 1, v[204:205]
	v_ashrrev_i32_e32 v241, 31, v240
	v_lshl_add_u64 v[122:123], s[58:59], 0, v[242:243]
	v_lshlrev_b64 v[244:245], 11, v[240:241]
	v_lshl_add_u64 v[114:115], v[122:123], 0, v[244:245]
	global_load_dwordx4 v[190:193], v[114:115], off
	global_load_dwordx4 v[186:189], v[114:115], off offset:256
	v_or_b32_e32 v236, 16, v240
	v_ashrrev_i32_e32 v237, 31, v236
	v_or_b32_e32 v232, 32, v240
	v_lshlrev_b64 v[238:239], 11, v[236:237]
	v_ashrrev_i32_e32 v233, 31, v232
	v_or_b32_e32 v228, 48, v240
	v_lshl_add_u64 v[114:115], v[122:123], 0, v[238:239]
	v_lshlrev_b64 v[234:235], 11, v[232:233]
	v_ashrrev_i32_e32 v229, 31, v228
	v_add_u32_e32 v224, 0x80, v240
	global_load_dwordx4 v[182:185], v[114:115], off
	global_load_dwordx4 v[178:181], v[114:115], off offset:256
	v_lshl_add_u64 v[114:115], v[122:123], 0, v[234:235]
	v_lshlrev_b64 v[230:231], 11, v[228:229]
	v_ashrrev_i32_e32 v225, 31, v224
	v_add_u32_e32 v220, 0x90, v240
	global_load_dwordx4 v[174:177], v[114:115], off
	global_load_dwordx4 v[170:173], v[114:115], off offset:256
	v_lshl_add_u64 v[114:115], v[122:123], 0, v[230:231]
	v_lshlrev_b64 v[226:227], 11, v[224:225]
	v_ashrrev_i32_e32 v221, 31, v220
	v_add_u32_e32 v216, 0xa0, v240
	v_add_u32_e32 v212, 0xb0, v240
	global_load_dwordx4 v[166:169], v[114:115], off
	global_load_dwordx4 v[162:165], v[114:115], off offset:256
	v_lshl_add_u64 v[114:115], v[122:123], 0, v[226:227]
	v_lshlrev_b64 v[222:223], 11, v[220:221]
	v_ashrrev_i32_e32 v217, 31, v216
	v_ashrrev_i32_e32 v213, 31, v212
	global_load_dwordx4 v[158:161], v[114:115], off
	global_load_dwordx4 v[146:149], v[114:115], off offset:256
	v_lshl_add_u64 v[114:115], v[122:123], 0, v[222:223]
	v_lshlrev_b64 v[218:219], 11, v[216:217]
	v_lshlrev_b64 v[214:215], 11, v[212:213]
	global_load_dwordx4 v[142:145], v[114:115], off
	global_load_dwordx4 v[138:141], v[114:115], off offset:256
	v_lshl_add_u64 v[114:115], v[122:123], 0, v[218:219]
	v_lshl_add_u64 v[122:123], v[122:123], 0, v[214:215]
	global_load_dwordx4 v[126:129], v[114:115], off
	s_nop 0
	global_load_dwordx4 v[114:117], v[114:115], off offset:256
	s_nop 0
	global_load_dwordx4 v[130:133], v[122:123], off
	s_nop 0
	global_load_dwordx4 v[122:125], v[122:123], off offset:256
	s_lshl_b32 s86, s12, 2
	s_ashr_i32 s87, s86, 31
	s_waitcnt vmcnt(0)
	v_lshlrev_b32_e32 v208, 16, v190
	v_and_b32_e32 v209, 0xffff0000, v190
	v_lshlrev_b32_e32 v190, 16, v191
	v_and_b32_e32 v191, 0xffff0000, v191
	v_lshlrev_b32_e32 v210, 16, v192
	v_and_b32_e32 v211, 0xffff0000, v192
	v_lshlrev_b32_e32 v192, 16, v193
	v_and_b32_e32 v193, 0xffff0000, v193
	v_pk_add_f32 v[154:155], v[154:155], v[208:209]
	v_lshl_add_u64 v[208:209], s[58:59], 0, v[244:245]
	v_pk_add_f32 v[156:157], v[156:157], v[190:191]
	v_pk_add_f32 v[190:191], v[152:153], v[192:193]
	v_pk_add_f32 v[192:193], v[150:151], v[210:211]
	v_cvt_pk_bf16_f32 v150, v154, v155
	v_cvt_pk_bf16_f32 v151, v156, v157
	v_lshl_add_u64 v[208:209], v[208:209], 0, v[242:243]
	v_cvt_pk_bf16_f32 v152, v192, v193
	v_cvt_pk_bf16_f32 v153, v190, v191
	global_store_dwordx4 v[208:209], v[150:153], off
	s_nop 1
	v_mul_f32_e32 v150, v155, v155
	v_mul_f32_e32 v151, v157, v157
	v_fmac_f32_e32 v150, v154, v154
	v_fmac_f32_e32 v151, v156, v156
	v_add_f32_e32 v150, v150, v151
	v_mul_f32_e32 v151, v193, v193
	v_mul_f32_e32 v152, v191, v191
	v_fmac_f32_e32 v151, v192, v192
	v_fmac_f32_e32 v152, v190, v190
	v_add_f32_e32 v151, v151, v152
	v_add_f32_e32 v190, v150, v151
	v_lshlrev_b32_e32 v150, 16, v186
	v_and_b32_e32 v151, 0xffff0000, v186
	v_lshlrev_b32_e32 v152, 16, v187
	v_and_b32_e32 v153, 0xffff0000, v187
	v_lshlrev_b32_e32 v154, 16, v188
	v_and_b32_e32 v155, 0xffff0000, v188
	v_lshlrev_b32_e32 v156, 16, v189
	v_and_b32_e32 v157, 0xffff0000, v189
	v_pk_add_f32 v[136:137], v[136:137], v[152:153]
	v_pk_add_f32 v[134:135], v[134:135], v[150:151]
	v_pk_add_f32 v[152:153], v[118:119], v[154:155]
	v_cvt_pk_bf16_f32 v118, v134, v135
	v_cvt_pk_bf16_f32 v119, v136, v137
	v_pk_add_f32 v[150:151], v[120:121], v[156:157]
	v_cvt_pk_bf16_f32 v120, v152, v153
	s_nop 0
	v_cvt_pk_bf16_f32 v121, v150, v151
	global_store_dwordx4 v[208:209], v[118:121], off offset:256
	s_nop 1
	v_mul_f32_e32 v118, v135, v135
	v_mul_f32_e32 v119, v137, v137
	v_fmac_f32_e32 v118, v134, v134
	v_fmac_f32_e32 v119, v136, v136
	v_add_f32_e32 v118, v118, v119
	v_mul_f32_e32 v119, v153, v153
	v_mul_f32_e32 v120, v151, v151
	v_fmac_f32_e32 v119, v152, v152
	v_fmac_f32_e32 v120, v150, v150
	v_add_f32_e32 v119, v119, v120
	v_add_f32_e32 v118, v118, v119
	v_and_b32_e32 v120, 64, v246
	v_add_f32_e32 v119, v190, v118
	v_xor_b32_e32 v118, 16, v246
	v_add_u32_e32 v121, 64, v120
	v_cmp_lt_i32_e32 vcc, v118, v121
	s_nop 1
	v_cndmask_b32_e32 v118, v246, v118, vcc
	v_lshlrev_b32_e32 v118, 2, v118
	v_mov_b32_e32 v120, v119
	s_nop 1
	v_permlane16_swap_b32_e32 v119, v120
	s_waitcnt lgkmcnt(0)
	v_add_f32_e32 v120, v119, v120
	v_xor_b32_e32 v119, 32, v246
	v_cmp_lt_i32_e32 vcc, v119, v121
	s_nop 1
	v_cndmask_b32_e32 v119, v246, v119, vcc
	v_lshlrev_b32_e32 v119, 2, v119
	v_mov_b32_e32 v121, v120
	s_nop 1
	v_permlane32_swap_b32_e32 v120, v121
	s_and_saveexec_b64 s[88:89], s[4:5]
	s_cbranch_execz .LBB0_325
	s_waitcnt lgkmcnt(0)
	v_add_f32_e32 v134, v120, v121
	v_lshlrev_b64 v[120:121], 6, v[240:241]
	v_lshl_add_u64 v[120:121], s[56:57], 0, v[120:121]
	v_lshl_add_u64 v[120:121], s[86:87], 2, v[120:121]
	s_lshl_b32 s12, s29, 2
	v_lshl_add_u64 v[120:121], v[120:121], 0, s[12:13]
	global_store_dword v[120:121], v134, off
; __device__ __forceinline__ unsigned cvt_pk_bf16(float lo, float hi) { unsigned r; asm volatile("v_cvt_pk_bf16_f32 %0, %1, %2" : "=v"(r) : "v"(lo), "v"(hi)); return r; }
;     __device__ __forceinline__ void operator()(const f32x4 (&acc)[2][2][4][2], const Unit& u, int wr, int wc, int fr, int fq) const {
;     ...
;             for (int m = 0; m < 4; ++m) { const int row = row0 + ai * HALF + m * 16; float s = 0.f;
; #pragma unroll
;                 for (int bj = 0; bj < 2; ++bj) { const size_t off = (size_t)row * 1024 + col0 + bj * HALF;
;                     const u32x4 h4 = hv[ai][m][bj];
;                     const f32x4 b0 = {__uint_as_float(h4.x << 16), __uint_as_float(h4.x & 0xffff0000u), __uint_as_float(h4.y << 16), __uint_as_float(h4.y & 0xffff0000u)};
;                     const f32x4 b1 = {__uint_as_float(h4.z << 16), __uint_as_float(h4.z & 0xffff0000u), __uint_as_float(h4.w << 16), __uint_as_float(h4.w & 0xffff0000u)};
;                     const f32x4 v0 = acc[ai][bj][m][0] + b0, v1 = acc[ai][bj][m][1] + b1;
;                     u32x4 w; w.x = cvt_pk_bf16(v0[0], v0[1]); w.y = cvt_pk_bf16(v0[2], v0[3]); w.z = cvt_pk_bf16(v1[0], v1[1]); w.w = cvt_pk_bf16(v1[2], v1[3]);
;                     *(u32x4*)(hb + off) = w;
;                     s += ((v0[0] * v0[0] + v0[1] * v0[1]) + (v0[2] * v0[2] + v0[3] * v0[3])) + ((v1[0] * v1[0] + v1[1] * v1[1]) + (v1[2] * v1[2] + v1[3] * v1[3])); }
;                 s += __shfl_xor(s, 16); s += __shfl_xor(s, 32);
;                 if (fq == 0) ssq[(size_t)row * 16 + u.pn * 4 + wc] = s; }
.LBB0_325:
	s_or_b64 exec, exec, s[88:89]
	v_lshlrev_b32_e32 v120, 16, v182
	s_waitcnt lgkmcnt(0)
	v_and_b32_e32 v121, 0xffff0000, v182
	v_lshlrev_b32_e32 v134, 16, v183
	v_and_b32_e32 v135, 0xffff0000, v183
	v_lshlrev_b32_e32 v136, 16, v184
	v_and_b32_e32 v137, 0xffff0000, v184
	v_pk_add_f32 v[110:111], v[110:111], v[120:121]
	v_pk_add_f32 v[112:113], v[112:113], v[134:135]
	v_pk_add_f32 v[134:135], v[106:107], v[136:137]
	v_cvt_pk_bf16_f32 v106, v110, v111
	v_mul_f32_e32 v111, v111, v111
	v_lshlrev_b32_e32 v150, 16, v185
	v_and_b32_e32 v151, 0xffff0000, v185
	v_fmac_f32_e32 v111, v110, v110
	v_mul_f32_e32 v110, v113, v113
	v_pk_add_f32 v[120:121], v[108:109], v[150:151]
	v_fmac_f32_e32 v110, v112, v112
	v_cvt_pk_bf16_f32 v107, v112, v113
	v_add_f32_e32 v110, v111, v110
	v_mul_f32_e32 v111, v135, v135
	v_mul_f32_e32 v112, v121, v121
	v_fmac_f32_e32 v111, v134, v134
	v_fmac_f32_e32 v112, v120, v120
	v_add_f32_e32 v111, v111, v112
	v_add_f32_e32 v136, v110, v111
	v_lshlrev_b32_e32 v110, 16, v178
	v_and_b32_e32 v111, 0xffff0000, v178
	v_lshlrev_b32_e32 v112, 16, v179
	v_and_b32_e32 v113, 0xffff0000, v179
	v_cvt_pk_bf16_f32 v108, v134, v135
	v_cvt_pk_bf16_f32 v109, v120, v121
	v_lshlrev_b32_e32 v120, 16, v180
	v_and_b32_e32 v121, 0xffff0000, v180
	v_pk_add_f32 v[104:105], v[104:105], v[112:113]
	v_pk_add_f32 v[102:103], v[102:103], v[110:111]
	v_lshlrev_b32_e32 v134, 16, v181
	v_and_b32_e32 v135, 0xffff0000, v181
	v_pk_add_f32 v[112:113], v[98:99], v[120:121]
	v_mul_f32_e32 v98, v103, v103
	v_mul_f32_e32 v99, v105, v105
	v_pk_add_f32 v[110:111], v[100:101], v[134:135]
	v_fmac_f32_e32 v98, v102, v102
	v_fmac_f32_e32 v99, v104, v104
	v_add_f32_e32 v98, v98, v99
	v_mul_f32_e32 v99, v113, v113
	v_mul_f32_e32 v100, v111, v111
	v_fmac_f32_e32 v99, v112, v112
	v_fmac_f32_e32 v100, v110, v110
	v_add_f32_e32 v99, v99, v100
	v_add_f32_e32 v98, v98, v99
	v_add_f32_e32 v101, v136, v98
	v_mov_b32_e32 v134, v101
	s_nop 1
	v_permlane16_swap_b32_e32 v101, v134
	v_lshl_add_u64 v[98:99], s[58:59], 0, v[238:239]
	v_lshl_add_u64 v[120:121], v[204:205], 1, v[98:99]
	global_store_dwordx4 v[120:121], v[106:109], off
	v_cvt_pk_bf16_f32 v100, v102, v103
	s_waitcnt lgkmcnt(0)
	v_add_f32_e32 v98, v101, v134
	v_mov_b32_e32 v99, v98
	s_nop 1
	v_permlane32_swap_b32_e32 v98, v99
	v_cvt_pk_bf16_f32 v101, v104, v105
	v_cvt_pk_bf16_f32 v102, v112, v113
	v_cvt_pk_bf16_f32 v103, v110, v111
	global_store_dwordx4 v[120:121], v[100:103], off offset:256
	s_and_saveexec_b64 s[88:89], s[4:5]
	s_cbranch_execz .LBB0_327
	s_waitcnt lgkmcnt(0)
	v_add_f32_e32 v100, v98, v99
	v_lshlrev_b64 v[98:99], 6, v[236:237]
	v_lshl_add_u64 v[98:99], s[56:57], 0, v[98:99]
	v_lshl_add_u64 v[98:99], s[86:87], 2, v[98:99]
	s_lshl_b32 s12, s29, 2
	v_lshl_add_u64 v[98:99], v[98:99], 0, s[12:13]
	global_store_dword v[98:99], v100, off
.LBB0_327:
	s_or_b64 exec, exec, s[88:89]
	v_lshlrev_b32_e32 v98, 16, v174
	s_waitcnt lgkmcnt(0)
	v_and_b32_e32 v99, 0xffff0000, v174
	v_lshlrev_b32_e32 v100, 16, v175
	v_and_b32_e32 v101, 0xffff0000, v175
	v_lshlrev_b32_e32 v102, 16, v176
	v_and_b32_e32 v103, 0xffff0000, v176
	v_pk_add_f32 v[94:95], v[94:95], v[98:99]
	v_pk_add_f32 v[96:97], v[96:97], v[100:101]
	v_pk_add_f32 v[100:101], v[90:91], v[102:103]
	v_cvt_pk_bf16_f32 v90, v94, v95
	v_mul_f32_e32 v95, v95, v95
	v_lshlrev_b32_e32 v104, 16, v177
	v_and_b32_e32 v105, 0xffff0000, v177
	v_fmac_f32_e32 v95, v94, v94
	v_mul_f32_e32 v94, v97, v97
	v_pk_add_f32 v[98:99], v[92:93], v[104:105]
	v_fmac_f32_e32 v94, v96, v96
	v_cvt_pk_bf16_f32 v91, v96, v97
	v_add_f32_e32 v94, v95, v94
	v_mul_f32_e32 v95, v101, v101
	v_mul_f32_e32 v96, v99, v99
	v_fmac_f32_e32 v95, v100, v100
	v_fmac_f32_e32 v96, v98, v98
	v_add_f32_e32 v95, v95, v96
	v_add_f32_e32 v102, v94, v95
	v_lshlrev_b32_e32 v94, 16, v170
	v_and_b32_e32 v95, 0xffff0000, v170
	v_lshlrev_b32_e32 v96, 16, v171
	v_and_b32_e32 v97, 0xffff0000, v171
	v_cvt_pk_bf16_f32 v92, v100, v101
	v_cvt_pk_bf16_f32 v93, v98, v99
	v_lshlrev_b32_e32 v98, 16, v172
	v_and_b32_e32 v99, 0xffff0000, v172
	v_pk_add_f32 v[88:89], v[88:89], v[96:97]
	v_pk_add_f32 v[86:87], v[86:87], v[94:95]
	v_lshlrev_b32_e32 v100, 16, v173
	v_and_b32_e32 v101, 0xffff0000, v173
	v_pk_add_f32 v[96:97], v[82:83], v[98:99]
	v_mul_f32_e32 v82, v87, v87
	v_mul_f32_e32 v83, v89, v89
	v_pk_add_f32 v[94:95], v[84:85], v[100:101]
	v_fmac_f32_e32 v82, v86, v86
	v_fmac_f32_e32 v83, v88, v88
	v_add_f32_e32 v82, v82, v83
	v_mul_f32_e32 v83, v97, v97
	v_mul_f32_e32 v84, v95, v95
	v_fmac_f32_e32 v83, v96, v96
	v_fmac_f32_e32 v84, v94, v94
	v_add_f32_e32 v83, v83, v84
	v_add_f32_e32 v82, v82, v83
	v_add_f32_e32 v85, v102, v82
	v_mov_b32_e32 v100, v85
	s_nop 1
	v_permlane16_swap_b32_e32 v85, v100
	v_lshl_add_u64 v[82:83], s[58:59], 0, v[234:235]
	v_lshl_add_u64 v[98:99], v[204:205], 1, v[82:83]
	global_store_dwordx4 v[98:99], v[90:93], off
	v_cvt_pk_bf16_f32 v84, v86, v87
	s_waitcnt lgkmcnt(0)
	v_add_f32_e32 v82, v85, v100
	v_mov_b32_e32 v83, v82
	s_nop 1
	v_permlane32_swap_b32_e32 v82, v83
	v_cvt_pk_bf16_f32 v85, v88, v89
	v_cvt_pk_bf16_f32 v86, v96, v97
	v_cvt_pk_bf16_f32 v87, v94, v95
	global_store_dwordx4 v[98:99], v[84:87], off offset:256
	s_and_saveexec_b64 s[88:89], s[4:5]
	s_cbranch_execz .LBB0_329
	s_waitcnt lgkmcnt(0)
	v_add_f32_e32 v84, v82, v83
	v_lshlrev_b64 v[82:83], 6, v[232:233]
	v_lshl_add_u64 v[82:83], s[56:57], 0, v[82:83]
	v_lshl_add_u64 v[82:83], s[86:87], 2, v[82:83]
	s_lshl_b32 s12, s29, 2
	v_lshl_add_u64 v[82:83], v[82:83], 0, s[12:13]
	global_store_dword v[82:83], v84, off
; __device__ __forceinline__ unsigned cvt_pk_bf16(float lo, float hi) { unsigned r; asm volatile("v_cvt_pk_bf16_f32 %0, %1, %2" : "=v"(r) : "v"(lo), "v"(hi)); return r; }
;     __device__ __forceinline__ void operator()(const f32x4 (&acc)[2][2][4][2], const Unit& u, int wr, int wc, int fr, int fq) const {
;     ...
;             for (int m = 0; m < 4; ++m) { const int row = row0 + ai * HALF + m * 16; float s = 0.f;
; #pragma unroll
;                 for (int bj = 0; bj < 2; ++bj) { const size_t off = (size_t)row * 1024 + col0 + bj * HALF;
;                     const u32x4 h4 = hv[ai][m][bj];
;                     const f32x4 b0 = {__uint_as_float(h4.x << 16), __uint_as_float(h4.x & 0xffff0000u), __uint_as_float(h4.y << 16), __uint_as_float(h4.y & 0xffff0000u)};
;                     const f32x4 b1 = {__uint_as_float(h4.z << 16), __uint_as_float(h4.z & 0xffff0000u), __uint_as_float(h4.w << 16), __uint_as_float(h4.w & 0xffff0000u)};
;                     const f32x4 v0 = acc[ai][bj][m][0] + b0, v1 = acc[ai][bj][m][1] + b1;
;                     u32x4 w; w.x = cvt_pk_bf16(v0[0], v0[1]); w.y = cvt_pk_bf16(v0[2], v0[3]); w.z = cvt_pk_bf16(v1[0], v1[1]); w.w = cvt_pk_bf16(v1[2], v1[3]);
;                     *(u32x4*)(hb + off) = w;
;                     s += ((v0[0] * v0[0] + v0[1] * v0[1]) + (v0[2] * v0[2] + v0[3] * v0[3])) + ((v1[0] * v1[0] + v1[1] * v1[1]) + (v1[2] * v1[2] + v1[3] * v1[3])); }
;                 s += __shfl_xor(s, 16); s += __shfl_xor(s, 32);
;                 if (fq == 0) ssq[(size_t)row * 16 + u.pn * 4 + wc] = s; }
.LBB0_329:
	s_or_b64 exec, exec, s[88:89]
	v_lshlrev_b32_e32 v82, 16, v166
	s_waitcnt lgkmcnt(0)
	v_and_b32_e32 v83, 0xffff0000, v166
	v_lshlrev_b32_e32 v84, 16, v167
	v_and_b32_e32 v85, 0xffff0000, v167
	v_lshlrev_b32_e32 v86, 16, v168
	v_and_b32_e32 v87, 0xffff0000, v168
	v_pk_add_f32 v[78:79], v[78:79], v[82:83]
	v_pk_add_f32 v[80:81], v[80:81], v[84:85]
	v_pk_add_f32 v[84:85], v[74:75], v[86:87]
	v_cvt_pk_bf16_f32 v74, v78, v79
	v_mul_f32_e32 v79, v79, v79
	v_lshlrev_b32_e32 v88, 16, v169
	v_and_b32_e32 v89, 0xffff0000, v169
	v_fmac_f32_e32 v79, v78, v78
	v_mul_f32_e32 v78, v81, v81
	v_pk_add_f32 v[82:83], v[76:77], v[88:89]
	v_fmac_f32_e32 v78, v80, v80
	v_cvt_pk_bf16_f32 v75, v80, v81
	v_add_f32_e32 v78, v79, v78
	v_mul_f32_e32 v79, v85, v85
	v_mul_f32_e32 v80, v83, v83
	v_fmac_f32_e32 v79, v84, v84
	v_fmac_f32_e32 v80, v82, v82
	v_add_f32_e32 v79, v79, v80
	v_add_f32_e32 v86, v78, v79
	v_lshlrev_b32_e32 v78, 16, v162
	v_and_b32_e32 v79, 0xffff0000, v162
	v_lshlrev_b32_e32 v80, 16, v163
	v_and_b32_e32 v81, 0xffff0000, v163
	v_cvt_pk_bf16_f32 v76, v84, v85
	v_cvt_pk_bf16_f32 v77, v82, v83
	v_lshlrev_b32_e32 v82, 16, v164
	v_and_b32_e32 v83, 0xffff0000, v164
	v_pk_add_f32 v[72:73], v[72:73], v[80:81]
	v_pk_add_f32 v[70:71], v[70:71], v[78:79]
	v_lshlrev_b32_e32 v84, 16, v165
	v_and_b32_e32 v85, 0xffff0000, v165
	v_pk_add_f32 v[80:81], v[66:67], v[82:83]
	v_mul_f32_e32 v66, v71, v71
	v_mul_f32_e32 v67, v73, v73
	v_pk_add_f32 v[78:79], v[68:69], v[84:85]
	v_fmac_f32_e32 v66, v70, v70
	v_fmac_f32_e32 v67, v72, v72
	v_add_f32_e32 v66, v66, v67
	v_mul_f32_e32 v67, v81, v81
	v_mul_f32_e32 v68, v79, v79
	v_fmac_f32_e32 v67, v80, v80
	v_fmac_f32_e32 v68, v78, v78
	v_add_f32_e32 v67, v67, v68
	v_add_f32_e32 v66, v66, v67
	v_add_f32_e32 v69, v86, v66
	v_mov_b32_e32 v84, v69
	s_nop 1
	v_permlane16_swap_b32_e32 v69, v84
	v_lshl_add_u64 v[66:67], s[58:59], 0, v[230:231]
	v_lshl_add_u64 v[82:83], v[204:205], 1, v[66:67]
	global_store_dwordx4 v[82:83], v[74:77], off
	v_cvt_pk_bf16_f32 v68, v70, v71
	s_waitcnt lgkmcnt(0)
	v_add_f32_e32 v66, v69, v84
	v_mov_b32_e32 v67, v66
	s_nop 1
	v_permlane32_swap_b32_e32 v66, v67
	v_cvt_pk_bf16_f32 v69, v72, v73
	v_cvt_pk_bf16_f32 v70, v80, v81
	v_cvt_pk_bf16_f32 v71, v78, v79
	global_store_dwordx4 v[82:83], v[68:71], off offset:256
	s_and_saveexec_b64 s[88:89], s[4:5]
	s_cbranch_execz .LBB0_331
	s_waitcnt lgkmcnt(0)
	v_add_f32_e32 v68, v66, v67
	v_lshlrev_b64 v[66:67], 6, v[228:229]
	v_lshl_add_u64 v[66:67], s[56:57], 0, v[66:67]
	v_lshl_add_u64 v[66:67], s[86:87], 2, v[66:67]
	s_lshl_b32 s12, s29, 2
	v_lshl_add_u64 v[66:67], v[66:67], 0, s[12:13]
	global_store_dword v[66:67], v68, off
.LBB0_331:
	s_or_b64 exec, exec, s[88:89]
	v_lshlrev_b32_e32 v66, 16, v158
	s_waitcnt lgkmcnt(0)
	v_and_b32_e32 v67, 0xffff0000, v158
	v_lshlrev_b32_e32 v68, 16, v159
	v_and_b32_e32 v69, 0xffff0000, v159
	v_lshlrev_b32_e32 v70, 16, v160
	v_and_b32_e32 v71, 0xffff0000, v160
	v_pk_add_f32 v[62:63], v[62:63], v[66:67]
	v_pk_add_f32 v[64:65], v[64:65], v[68:69]
	v_pk_add_f32 v[68:69], v[58:59], v[70:71]
	v_cvt_pk_bf16_f32 v58, v62, v63
	v_mul_f32_e32 v63, v63, v63
	v_lshlrev_b32_e32 v72, 16, v161
	v_and_b32_e32 v73, 0xffff0000, v161
	v_fmac_f32_e32 v63, v62, v62
	v_mul_f32_e32 v62, v65, v65
	v_pk_add_f32 v[66:67], v[60:61], v[72:73]
	v_fmac_f32_e32 v62, v64, v64
	v_cvt_pk_bf16_f32 v59, v64, v65
	v_add_f32_e32 v62, v63, v62
	v_mul_f32_e32 v63, v69, v69
	v_mul_f32_e32 v64, v67, v67
	v_fmac_f32_e32 v63, v68, v68
	v_fmac_f32_e32 v64, v66, v66
	v_add_f32_e32 v63, v63, v64
	v_add_f32_e32 v70, v62, v63
	v_lshlrev_b32_e32 v62, 16, v146
	v_and_b32_e32 v63, 0xffff0000, v146
	v_lshlrev_b32_e32 v64, 16, v147
	v_and_b32_e32 v65, 0xffff0000, v147
	v_cvt_pk_bf16_f32 v60, v68, v69
	v_cvt_pk_bf16_f32 v61, v66, v67
	v_lshlrev_b32_e32 v66, 16, v148
	v_and_b32_e32 v67, 0xffff0000, v148
	v_pk_add_f32 v[56:57], v[56:57], v[64:65]
	v_pk_add_f32 v[54:55], v[54:55], v[62:63]
	v_lshlrev_b32_e32 v68, 16, v149
	v_and_b32_e32 v69, 0xffff0000, v149
	v_pk_add_f32 v[64:65], v[50:51], v[66:67]
	v_mul_f32_e32 v50, v55, v55
	v_mul_f32_e32 v51, v57, v57
	v_pk_add_f32 v[62:63], v[52:53], v[68:69]
	v_fmac_f32_e32 v50, v54, v54
	v_fmac_f32_e32 v51, v56, v56
	v_add_f32_e32 v50, v50, v51
	v_mul_f32_e32 v51, v65, v65
	v_mul_f32_e32 v52, v63, v63
	v_fmac_f32_e32 v51, v64, v64
	v_fmac_f32_e32 v52, v62, v62
	v_add_f32_e32 v51, v51, v52
	v_add_f32_e32 v50, v50, v51
	v_add_f32_e32 v53, v70, v50
	v_mov_b32_e32 v68, v53
	s_nop 1
	v_permlane16_swap_b32_e32 v53, v68
	v_lshl_add_u64 v[50:51], s[58:59], 0, v[226:227]
	v_lshl_add_u64 v[66:67], v[204:205], 1, v[50:51]
	global_store_dwordx4 v[66:67], v[58:61], off
	v_cvt_pk_bf16_f32 v52, v54, v55
	s_waitcnt lgkmcnt(0)
	v_add_f32_e32 v50, v53, v68
	v_mov_b32_e32 v51, v50
	s_nop 1
	v_permlane32_swap_b32_e32 v50, v51
	v_cvt_pk_bf16_f32 v53, v56, v57
	v_cvt_pk_bf16_f32 v54, v64, v65
	v_cvt_pk_bf16_f32 v55, v62, v63
	global_store_dwordx4 v[66:67], v[52:55], off offset:256
	s_and_saveexec_b64 s[88:89], s[4:5]
	s_cbranch_execz .LBB0_333
	s_waitcnt lgkmcnt(0)
	v_add_f32_e32 v52, v50, v51
	v_lshlrev_b64 v[50:51], 6, v[224:225]
	v_lshl_add_u64 v[50:51], s[56:57], 0, v[50:51]
	v_lshl_add_u64 v[50:51], s[86:87], 2, v[50:51]
	s_lshl_b32 s12, s29, 2
	v_lshl_add_u64 v[50:51], v[50:51], 0, s[12:13]
	global_store_dword v[50:51], v52, off
; __device__ __forceinline__ unsigned cvt_pk_bf16(float lo, float hi) { unsigned r; asm volatile("v_cvt_pk_bf16_f32 %0, %1, %2" : "=v"(r) : "v"(lo), "v"(hi)); return r; }
;     __device__ __forceinline__ void operator()(const f32x4 (&acc)[2][2][4][2], const Unit& u, int wr, int wc, int fr, int fq) const {
;     ...
;             for (int m = 0; m < 4; ++m) { const int row = row0 + ai * HALF + m * 16; float s = 0.f;
; #pragma unroll
;                 for (int bj = 0; bj < 2; ++bj) { const size_t off = (size_t)row * 1024 + col0 + bj * HALF;
;                     const u32x4 h4 = hv[ai][m][bj];
;                     const f32x4 b0 = {__uint_as_float(h4.x << 16), __uint_as_float(h4.x & 0xffff0000u), __uint_as_float(h4.y << 16), __uint_as_float(h4.y & 0xffff0000u)};
;                     const f32x4 b1 = {__uint_as_float(h4.z << 16), __uint_as_float(h4.z & 0xffff0000u), __uint_as_float(h4.w << 16), __uint_as_float(h4.w & 0xffff0000u)};
;                     const f32x4 v0 = acc[ai][bj][m][0] + b0, v1 = acc[ai][bj][m][1] + b1;
;                     u32x4 w; w.x = cvt_pk_bf16(v0[0], v0[1]); w.y = cvt_pk_bf16(v0[2], v0[3]); w.z = cvt_pk_bf16(v1[0], v1[1]); w.w = cvt_pk_bf16(v1[2], v1[3]);
;                     *(u32x4*)(hb + off) = w;
;                     s += ((v0[0] * v0[0] + v0[1] * v0[1]) + (v0[2] * v0[2] + v0[3] * v0[3])) + ((v1[0] * v1[0] + v1[1] * v1[1]) + (v1[2] * v1[2] + v1[3] * v1[3])); }
;                 s += __shfl_xor(s, 16); s += __shfl_xor(s, 32);
;                 if (fq == 0) ssq[(size_t)row * 16 + u.pn * 4 + wc] = s; }
.LBB0_333:
	s_or_b64 exec, exec, s[88:89]
	v_lshlrev_b32_e32 v50, 16, v142
	s_waitcnt lgkmcnt(0)
	v_and_b32_e32 v51, 0xffff0000, v142
	v_lshlrev_b32_e32 v52, 16, v143
	v_and_b32_e32 v53, 0xffff0000, v143
	v_lshlrev_b32_e32 v54, 16, v144
	v_and_b32_e32 v55, 0xffff0000, v144
	v_pk_add_f32 v[46:47], v[46:47], v[50:51]
	v_pk_add_f32 v[48:49], v[48:49], v[52:53]
	v_pk_add_f32 v[52:53], v[42:43], v[54:55]
	v_cvt_pk_bf16_f32 v42, v46, v47
	v_mul_f32_e32 v47, v47, v47
	v_lshlrev_b32_e32 v56, 16, v145
	v_and_b32_e32 v57, 0xffff0000, v145
	v_fmac_f32_e32 v47, v46, v46
	v_mul_f32_e32 v46, v49, v49
	v_pk_add_f32 v[50:51], v[44:45], v[56:57]
	v_fmac_f32_e32 v46, v48, v48
	v_cvt_pk_bf16_f32 v43, v48, v49
	v_add_f32_e32 v46, v47, v46
	v_mul_f32_e32 v47, v53, v53
	v_mul_f32_e32 v48, v51, v51
	v_fmac_f32_e32 v47, v52, v52
	v_fmac_f32_e32 v48, v50, v50
	v_add_f32_e32 v47, v47, v48
	v_add_f32_e32 v54, v46, v47
	v_lshlrev_b32_e32 v46, 16, v138
	v_and_b32_e32 v47, 0xffff0000, v138
	v_lshlrev_b32_e32 v48, 16, v139
	v_and_b32_e32 v49, 0xffff0000, v139
	v_cvt_pk_bf16_f32 v44, v52, v53
	v_cvt_pk_bf16_f32 v45, v50, v51
	v_lshlrev_b32_e32 v50, 16, v140
	v_and_b32_e32 v51, 0xffff0000, v140
	v_pk_add_f32 v[40:41], v[40:41], v[48:49]
	v_pk_add_f32 v[38:39], v[38:39], v[46:47]
	v_lshlrev_b32_e32 v52, 16, v141
	v_and_b32_e32 v53, 0xffff0000, v141
	v_pk_add_f32 v[48:49], v[34:35], v[50:51]
	v_mul_f32_e32 v34, v39, v39
	v_mul_f32_e32 v35, v41, v41
	v_pk_add_f32 v[46:47], v[36:37], v[52:53]
	v_fmac_f32_e32 v34, v38, v38
	v_fmac_f32_e32 v35, v40, v40
	v_add_f32_e32 v34, v34, v35
	v_mul_f32_e32 v35, v49, v49
	v_mul_f32_e32 v36, v47, v47
	v_fmac_f32_e32 v35, v48, v48
	v_fmac_f32_e32 v36, v46, v46
	v_add_f32_e32 v35, v35, v36
	v_add_f32_e32 v34, v34, v35
	v_add_f32_e32 v37, v54, v34
	v_mov_b32_e32 v52, v37
	s_nop 1
	v_permlane16_swap_b32_e32 v37, v52
	v_lshl_add_u64 v[34:35], s[58:59], 0, v[222:223]
	v_lshl_add_u64 v[50:51], v[204:205], 1, v[34:35]
	global_store_dwordx4 v[50:51], v[42:45], off
	v_cvt_pk_bf16_f32 v36, v38, v39
	s_waitcnt lgkmcnt(0)
	v_add_f32_e32 v34, v37, v52
	v_mov_b32_e32 v35, v34
	s_nop 1
	v_permlane32_swap_b32_e32 v34, v35
	v_cvt_pk_bf16_f32 v37, v40, v41
	v_cvt_pk_bf16_f32 v38, v48, v49
	v_cvt_pk_bf16_f32 v39, v46, v47
	global_store_dwordx4 v[50:51], v[36:39], off offset:256
	s_and_saveexec_b64 s[88:89], s[4:5]
	s_cbranch_execz .LBB0_335
	s_waitcnt lgkmcnt(0)
	v_add_f32_e32 v36, v34, v35
	v_lshlrev_b64 v[34:35], 6, v[220:221]
	v_lshl_add_u64 v[34:35], s[56:57], 0, v[34:35]
	v_lshl_add_u64 v[34:35], s[86:87], 2, v[34:35]
	s_lshl_b32 s12, s29, 2
	v_lshl_add_u64 v[34:35], v[34:35], 0, s[12:13]
	global_store_dword v[34:35], v36, off
; __device__ __forceinline__ unsigned cvt_pk_bf16(float lo, float hi) { unsigned r; asm volatile("v_cvt_pk_bf16_f32 %0, %1, %2" : "=v"(r) : "v"(lo), "v"(hi)); return r; }
;     __device__ __forceinline__ void operator()(const f32x4 (&acc)[2][2][4][2], const Unit& u, int wr, int wc, int fr, int fq) const {
;     ...
;             for (int m = 0; m < 4; ++m) { const int row = row0 + ai * HALF + m * 16; float s = 0.f;
; #pragma unroll
;                 for (int bj = 0; bj < 2; ++bj) { const size_t off = (size_t)row * 1024 + col0 + bj * HALF;
;                     const u32x4 h4 = hv[ai][m][bj];
;                     const f32x4 b0 = {__uint_as_float(h4.x << 16), __uint_as_float(h4.x & 0xffff0000u), __uint_as_float(h4.y << 16), __uint_as_float(h4.y & 0xffff0000u)};
;                     const f32x4 b1 = {__uint_as_float(h4.z << 16), __uint_as_float(h4.z & 0xffff0000u), __uint_as_float(h4.w << 16), __uint_as_float(h4.w & 0xffff0000u)};
;                     const f32x4 v0 = acc[ai][bj][m][0] + b0, v1 = acc[ai][bj][m][1] + b1;
;                     u32x4 w; w.x = cvt_pk_bf16(v0[0], v0[1]); w.y = cvt_pk_bf16(v0[2], v0[3]); w.z = cvt_pk_bf16(v1[0], v1[1]); w.w = cvt_pk_bf16(v1[2], v1[3]);
;                     *(u32x4*)(hb + off) = w;
;                     s += ((v0[0] * v0[0] + v0[1] * v0[1]) + (v0[2] * v0[2] + v0[3] * v0[3])) + ((v1[0] * v1[0] + v1[1] * v1[1]) + (v1[2] * v1[2] + v1[3] * v1[3])); }
;                 s += __shfl_xor(s, 16); s += __shfl_xor(s, 32);
;                 if (fq == 0) ssq[(size_t)row * 16 + u.pn * 4 + wc] = s; }
.LBB0_335:
	s_or_b64 exec, exec, s[88:89]
	v_lshlrev_b32_e32 v34, 16, v126
	s_waitcnt lgkmcnt(0)
	v_and_b32_e32 v35, 0xffff0000, v126
	v_lshlrev_b32_e32 v36, 16, v127
	v_and_b32_e32 v37, 0xffff0000, v127
	v_lshlrev_b32_e32 v38, 16, v128
	v_and_b32_e32 v39, 0xffff0000, v128
	v_pk_add_f32 v[30:31], v[30:31], v[34:35]
	v_pk_add_f32 v[32:33], v[32:33], v[36:37]
	v_pk_add_f32 v[36:37], v[26:27], v[38:39]
	v_cvt_pk_bf16_f32 v26, v30, v31
	v_mul_f32_e32 v31, v31, v31
	v_lshlrev_b32_e32 v40, 16, v129
	v_and_b32_e32 v41, 0xffff0000, v129
	v_fmac_f32_e32 v31, v30, v30
	v_mul_f32_e32 v30, v33, v33
	v_pk_add_f32 v[34:35], v[28:29], v[40:41]
	v_fmac_f32_e32 v30, v32, v32
	v_cvt_pk_bf16_f32 v27, v32, v33
	v_add_f32_e32 v30, v31, v30
	v_mul_f32_e32 v31, v37, v37
	v_mul_f32_e32 v32, v35, v35
	v_fmac_f32_e32 v31, v36, v36
	v_fmac_f32_e32 v32, v34, v34
	v_add_f32_e32 v31, v31, v32
	v_add_f32_e32 v38, v30, v31
	v_lshlrev_b32_e32 v30, 16, v114
	v_and_b32_e32 v31, 0xffff0000, v114
	v_lshlrev_b32_e32 v32, 16, v115
	v_and_b32_e32 v33, 0xffff0000, v115
	v_cvt_pk_bf16_f32 v28, v36, v37
	v_cvt_pk_bf16_f32 v29, v34, v35
	v_lshlrev_b32_e32 v34, 16, v116
	v_and_b32_e32 v35, 0xffff0000, v116
	v_pk_add_f32 v[24:25], v[24:25], v[32:33]
	v_pk_add_f32 v[22:23], v[22:23], v[30:31]
	v_lshlrev_b32_e32 v36, 16, v117
	v_and_b32_e32 v37, 0xffff0000, v117
	v_pk_add_f32 v[32:33], v[18:19], v[34:35]
	v_mul_f32_e32 v18, v23, v23
	v_mul_f32_e32 v19, v25, v25
	v_pk_add_f32 v[30:31], v[20:21], v[36:37]
	v_fmac_f32_e32 v18, v22, v22
	v_fmac_f32_e32 v19, v24, v24
	v_add_f32_e32 v18, v18, v19
	v_mul_f32_e32 v19, v33, v33
	v_mul_f32_e32 v20, v31, v31
	v_fmac_f32_e32 v19, v32, v32
	v_fmac_f32_e32 v20, v30, v30
	v_add_f32_e32 v19, v19, v20
	v_add_f32_e32 v18, v18, v19
	v_add_f32_e32 v21, v38, v18
	v_mov_b32_e32 v36, v21
	s_nop 1
	v_permlane16_swap_b32_e32 v21, v36
	v_lshl_add_u64 v[18:19], s[58:59], 0, v[218:219]
	v_lshl_add_u64 v[34:35], v[204:205], 1, v[18:19]
	global_store_dwordx4 v[34:35], v[26:29], off
	v_cvt_pk_bf16_f32 v20, v22, v23
	s_waitcnt lgkmcnt(0)
	v_add_f32_e32 v18, v21, v36
	v_mov_b32_e32 v19, v18
	s_nop 1
	v_permlane32_swap_b32_e32 v18, v19
	v_cvt_pk_bf16_f32 v21, v24, v25
	v_cvt_pk_bf16_f32 v22, v32, v33
	v_cvt_pk_bf16_f32 v23, v30, v31
	global_store_dwordx4 v[34:35], v[20:23], off offset:256
	s_and_saveexec_b64 s[88:89], s[4:5]
	s_cbranch_execz .LBB0_337
	s_waitcnt lgkmcnt(0)
	v_add_f32_e32 v20, v18, v19
	v_lshlrev_b64 v[18:19], 6, v[216:217]
	v_lshl_add_u64 v[18:19], s[56:57], 0, v[18:19]
	v_lshl_add_u64 v[18:19], s[86:87], 2, v[18:19]
	s_lshl_b32 s12, s29, 2
	v_lshl_add_u64 v[18:19], v[18:19], 0, s[12:13]
	global_store_dword v[18:19], v20, off
.LBB0_337:
	s_or_b64 exec, exec, s[88:89]
	v_lshlrev_b32_e32 v18, 16, v130
	s_waitcnt lgkmcnt(0)
	v_and_b32_e32 v19, 0xffff0000, v130
	v_lshlrev_b32_e32 v20, 16, v131
	v_and_b32_e32 v21, 0xffff0000, v131
	v_lshlrev_b32_e32 v22, 16, v132
	v_and_b32_e32 v23, 0xffff0000, v132
	v_pk_add_f32 v[14:15], v[14:15], v[18:19]
	v_pk_add_f32 v[16:17], v[16:17], v[20:21]
	v_pk_add_f32 v[20:21], v[10:11], v[22:23]
	v_cvt_pk_bf16_f32 v10, v14, v15
	v_mul_f32_e32 v15, v15, v15
	v_lshlrev_b32_e32 v24, 16, v133
	v_and_b32_e32 v25, 0xffff0000, v133
	v_fmac_f32_e32 v15, v14, v14
	v_mul_f32_e32 v14, v17, v17
	v_pk_add_f32 v[18:19], v[12:13], v[24:25]
	v_fmac_f32_e32 v14, v16, v16
	v_cvt_pk_bf16_f32 v11, v16, v17
	v_add_f32_e32 v14, v15, v14
	v_mul_f32_e32 v15, v21, v21
	v_mul_f32_e32 v16, v19, v19
	v_fmac_f32_e32 v15, v20, v20
	v_fmac_f32_e32 v16, v18, v18
	v_add_f32_e32 v15, v15, v16
	v_add_f32_e32 v22, v14, v15
	v_lshlrev_b32_e32 v14, 16, v122
	v_and_b32_e32 v15, 0xffff0000, v122
	v_lshlrev_b32_e32 v16, 16, v123
	v_and_b32_e32 v17, 0xffff0000, v123
	v_cvt_pk_bf16_f32 v12, v20, v21
	v_cvt_pk_bf16_f32 v13, v18, v19
	v_lshlrev_b32_e32 v18, 16, v124
	v_and_b32_e32 v19, 0xffff0000, v124
	v_pk_add_f32 v[8:9], v[8:9], v[16:17]
	v_pk_add_f32 v[6:7], v[6:7], v[14:15]
	v_lshlrev_b32_e32 v20, 16, v125
	v_and_b32_e32 v21, 0xffff0000, v125
	v_pk_add_f32 v[16:17], v[2:3], v[18:19]
	v_mul_f32_e32 v2, v7, v7
	v_mul_f32_e32 v3, v9, v9
	v_pk_add_f32 v[14:15], v[4:5], v[20:21]
	v_fmac_f32_e32 v2, v6, v6
	v_fmac_f32_e32 v3, v8, v8
	v_add_f32_e32 v2, v2, v3
	v_mul_f32_e32 v3, v17, v17
	v_mul_f32_e32 v4, v15, v15
	v_fmac_f32_e32 v3, v16, v16
	v_fmac_f32_e32 v4, v14, v14
	v_add_f32_e32 v3, v3, v4
	v_add_f32_e32 v2, v2, v3
	v_add_f32_e32 v5, v22, v2
	v_mov_b32_e32 v20, v5
	s_nop 1
	v_permlane16_swap_b32_e32 v5, v20
	v_lshl_add_u64 v[2:3], s[58:59], 0, v[214:215]
	v_lshl_add_u64 v[18:19], v[204:205], 1, v[2:3]
	global_store_dwordx4 v[18:19], v[10:13], off
	v_cvt_pk_bf16_f32 v4, v6, v7
	s_waitcnt lgkmcnt(0)
	v_add_f32_e32 v2, v5, v20
	v_mov_b32_e32 v3, v2
	s_nop 1
	v_permlane32_swap_b32_e32 v2, v3
	v_cvt_pk_bf16_f32 v5, v8, v9
	v_cvt_pk_bf16_f32 v6, v16, v17
	v_cvt_pk_bf16_f32 v7, v14, v15
	global_store_dwordx4 v[18:19], v[4:7], off offset:256
	s_and_saveexec_b64 s[88:89], s[4:5]
	s_cbranch_execz .LBB0_339
	s_waitcnt lgkmcnt(0)
	v_add_f32_e32 v4, v2, v3
	v_lshlrev_b64 v[2:3], 6, v[212:213]
	v_lshl_add_u64 v[2:3], s[56:57], 0, v[2:3]
	v_lshl_add_u64 v[2:3], s[86:87], 2, v[2:3]
	s_lshl_b32 s12, s29, 2
	v_lshl_add_u64 v[2:3], v[2:3], 0, s[12:13]
	global_store_dword v[2:3], v4, off
